# the 64 s5_in layer-1 weight tiles converted in qkv(0) by the fast V-tile workgroups (two each); ffn_in(1) idle workgroups convert 7 tiles instead of 8
# baseline (speedup 1.0000x reference)
.Lwh_entry:
	s_cmp_lg_u32 s54, 8
	s_cbranch_scc1 .LBB0_664
	s_mov_b32 s46, s0
	s_mov_b32 s33, 0
	s_cmpk_lt_i32 s0, 0x80
	s_cbranch_scc1 .Lwh_go
	s_cmpk_lt_i32 s0, 0x90
	s_cbranch_scc1 .LBB0_664
	s_cmpk_lt_i32 s0, 0xb0
	s_cbranch_scc1 .Lwh_go
	s_sub_i32 s0, s0, 48
.Lwh_go:
	s_mov_b64 exec, -1
	s_waitcnt lgkmcnt(0)
	s_barrier
	s_lshr_b32 s4, s0, 4
	s_and_b32 s5, s0, 15
	s_cmp_eq_u32 s33, 0
	s_cbranch_scc0 .Lwh_m1
	s_load_dwordx2 s[24:25], s[72:73], 0xd8
	s_mov_b32 s40, 0x1600000
	s_mov_b32 s41, 0x5104000
	s_mov_b32 s42, 0x58000
	s_movk_i32 s43, 0x1600
	s_branch .Lwh_m
.Lwh_m1:
	s_load_dwordx2 s[24:25], s[72:73], 0x58
	s_mov_b32 s40, 0x400000
	s_mov_b32 s41, 0x204000
	s_mov_b32 s42, 0x20000
	s_movk_i32 s43, 0x800
.Lwh_m:
	s_lshl_b32 s28, s4, 20
	s_lshl_b32 s29, s5, 8
	s_add_u32 s28, s28, s29
	s_add_u32 s28, s28, s40
	s_waitcnt lgkmcnt(0)
	s_add_u32 s24, s24, s28
	s_addc_u32 s25, s25, 0
	v_lshrrev_b32_e32 v40, 4, v156
	v_and_b32_e32 v41, 15, v156
	v_lshlrev_b32_e32 v41, 4, v41
	v_lshl_add_u32 v42, v40, 12, v41
	global_load_dwordx4 v[0:3], v42, s[24:25] nt
	s_add_u32 s24, s24, 0x20000
	s_addc_u32 s25, s25, 0
	global_load_dwordx4 v[4:7], v42, s[24:25] nt
	s_add_u32 s24, s24, 0x20000
	s_addc_u32 s25, s25, 0
	global_load_dwordx4 v[8:11], v42, s[24:25] nt
	s_add_u32 s24, s24, 0x20000
	s_addc_u32 s25, s25, 0
	global_load_dwordx4 v[12:15], v42, s[24:25] nt
	s_add_u32 s24, s24, 0x20000
	s_addc_u32 s25, s25, 0
	global_load_dwordx4 v[16:19], v42, s[24:25] nt
	s_add_u32 s24, s24, 0x20000
	s_addc_u32 s25, s25, 0
	global_load_dwordx4 v[20:23], v42, s[24:25] nt
	s_add_u32 s24, s24, 0x20000
	s_addc_u32 s25, s25, 0
	global_load_dwordx4 v[24:27], v42, s[24:25] nt
	s_add_u32 s24, s24, 0x20000
	s_addc_u32 s25, s25, 0
	global_load_dwordx4 v[28:31], v42, s[24:25] nt
	v_mul_u32_u24_e32 v43, 0x104, v40
	v_add_u32_e32 v43, v43, v41
	s_waitcnt vmcnt(7)
	ds_write2_b32 v43, v0, v1 offset1:1
	ds_write2_b32 v43, v2, v3 offset0:2 offset1:3
	v_add_u32_e32 v43, 0x2080, v43
	s_waitcnt vmcnt(6)
	ds_write2_b32 v43, v4, v5 offset1:1
	ds_write2_b32 v43, v6, v7 offset0:2 offset1:3
	v_add_u32_e32 v43, 0x2080, v43
	s_waitcnt vmcnt(5)
	ds_write2_b32 v43, v8, v9 offset1:1
	ds_write2_b32 v43, v10, v11 offset0:2 offset1:3
	v_add_u32_e32 v43, 0x2080, v43
	s_waitcnt vmcnt(4)
	ds_write2_b32 v43, v12, v13 offset1:1
	ds_write2_b32 v43, v14, v15 offset0:2 offset1:3
	v_add_u32_e32 v43, 0x2080, v43
	s_waitcnt vmcnt(3)
	ds_write2_b32 v43, v16, v17 offset1:1
	ds_write2_b32 v43, v18, v19 offset0:2 offset1:3
	v_add_u32_e32 v43, 0x2080, v43
	s_waitcnt vmcnt(2)
	ds_write2_b32 v43, v20, v21 offset1:1
	ds_write2_b32 v43, v22, v23 offset0:2 offset1:3
	v_add_u32_e32 v43, 0x2080, v43
	s_waitcnt vmcnt(1)
	ds_write2_b32 v43, v24, v25 offset1:1
	ds_write2_b32 v43, v26, v27 offset0:2 offset1:3
	v_add_u32_e32 v43, 0x2080, v43
	s_waitcnt vmcnt(0)
	ds_write2_b32 v43, v28, v29 offset1:1
	ds_write2_b32 v43, v30, v31 offset0:2 offset1:3
	s_waitcnt lgkmcnt(0)
	s_barrier
	v_lshrrev_b32_e32 v40, 3, v156
	v_and_b32_e32 v41, 7, v156
	v_mul_u32_u24_e32 v45, 0x820, v41
	v_lshl_add_u32 v45, v40, 2, v45
	v_and_b32_e32 v46, 32, v40
	v_bfe_u32 v47, v40, 2, 1
	v_lshl_add_u32 v46, v47, 4, v46
	v_bfe_u32 v47, v40, 3, 2
	v_lshl_add_u32 v46, v47, 2, v46
	v_and_b32_e32 v47, 3, v40
	v_add_u32_e32 v46, v46, v47
	s_cmp_eq_u32 s33, 0
	s_cbranch_scc1 .Lwh_r0
	v_mov_b32_e32 v46, v40
.Lwh_r0:
	v_mul_u32_u24_e32 v46, s43, v46
	v_lshl_add_u32 v46, v41, 4, v46
	s_mul_i32 s28, s5, s42
	s_lshl_b32 s29, s4, 9
	s_add_u32 s28, s28, s29
	s_add_u32 s28, s28, s41
	s_add_u32 s24, s48, s28
	s_addc_u32 s25, s49, 0
	v_add_u32_e32 v48, 0x0, v45
	ds_read2_b32 v[32:33], v48 offset1:65
	ds_read2_b32 v[34:35], v48 offset0:130 offset1:195
	v_add_u32_e32 v49, 0x410, v48
	ds_read2_b32 v[36:37], v49 offset1:65
	ds_read2_b32 v[38:39], v49 offset0:130 offset1:195
	s_waitcnt lgkmcnt(0)
	v_cvt_pk_bf16_f32 v32, v32, v33
	v_cvt_pk_bf16_f32 v33, v34, v35
	v_cvt_pk_bf16_f32 v34, v36, v37
	v_cvt_pk_bf16_f32 v35, v38, v39
	global_store_dwordx4 v46, v[32:35], s[24:25]
	s_nop 1
	v_add_u32_e32 v48, 0x4100, v45
	ds_read2_b32 v[32:33], v48 offset1:65
	ds_read2_b32 v[34:35], v48 offset0:130 offset1:195
	v_add_u32_e32 v49, 0x410, v48
	ds_read2_b32 v[36:37], v49 offset1:65
	ds_read2_b32 v[38:39], v49 offset0:130 offset1:195
	s_waitcnt lgkmcnt(0)
	v_cvt_pk_bf16_f32 v32, v32, v33
	v_cvt_pk_bf16_f32 v33, v34, v35
	v_cvt_pk_bf16_f32 v34, v36, v37
	v_cvt_pk_bf16_f32 v35, v38, v39
	global_store_dwordx4 v46, v[32:35], s[24:25] offset:128
	s_nop 1
	v_add_u32_e32 v48, 0x8200, v45
	ds_read2_b32 v[32:33], v48 offset1:65
	ds_read2_b32 v[34:35], v48 offset0:130 offset1:195
	v_add_u32_e32 v49, 0x410, v48
	ds_read2_b32 v[36:37], v49 offset1:65
	ds_read2_b32 v[38:39], v49 offset0:130 offset1:195
	s_waitcnt lgkmcnt(0)
	v_cvt_pk_bf16_f32 v32, v32, v33
	v_cvt_pk_bf16_f32 v33, v34, v35
	v_cvt_pk_bf16_f32 v34, v36, v37
	v_cvt_pk_bf16_f32 v35, v38, v39
	global_store_dwordx4 v46, v[32:35], s[24:25] offset:256
	s_nop 1
	v_add_u32_e32 v48, 0xc300, v45
	ds_read2_b32 v[32:33], v48 offset1:65
	ds_read2_b32 v[34:35], v48 offset0:130 offset1:195
	v_add_u32_e32 v49, 0x410, v48
	ds_read2_b32 v[36:37], v49 offset1:65
	ds_read2_b32 v[38:39], v49 offset0:130 offset1:195
	s_waitcnt lgkmcnt(0)
	v_cvt_pk_bf16_f32 v32, v32, v33
	v_cvt_pk_bf16_f32 v33, v34, v35
	v_cvt_pk_bf16_f32 v34, v36, v37
	v_cvt_pk_bf16_f32 v35, v38, v39
	global_store_dwordx4 v46, v[32:35], s[24:25] offset:384
	s_nop 1
	s_barrier
	s_cmpk_lt_i32 s46, 0xa0
	s_cbranch_scc1 .LBB0_664
	s_add_i32 s33, s33, 1
	s_cmp_gt_u32 s33, 2
	s_cbranch_scc1 .LBB0_664
	s_sub_i32 s0, s46, 0xa0
	s_lshl_b32 s0, s0, 1
	s_add_i32 s0, s0, s33
	s_add_i32 s0, s0, -1
	s_branch .Lwh_go

.LBB0_798:
	s_and_b32 s0, 0xffff, s5
	s_cmp_lg_u32 s0, 0
	s_cselect_b64 s[0:1], -1, 0
	s_cmp_lg_u64 s[0:1], 0
	s_addc_u32 s0, s4, 0
	s_cmpk_eq_i32 s0, 0x100
	s_cbranch_scc0 .LBB0_955
	v_readlane_b32 s0, v255, 6
	s_cmp_eq_u32 s0, 3
	v_readlane_b32 s4, v254, 0
	s_cselect_b64 s[0:1], -1, 0
	s_cmpk_lt_i32 s4, 0xc0
	s_cselect_b64 s[4:5], -1, 0
	s_or_b64 s[0:1], s[0:1], s[4:5]
	s_and_b64 vcc, exec, s[0:1]
	s_cbranch_vccnz .LBB0_955
	v_readlane_b32 s0, v255, 6
	s_cmp_eq_u32 s0, 1
	s_movk_i32 s0, 0x8d0
	s_cselect_b32 s4, s0, 0xa10
	s_movk_i32 s0, 0x650
	s_cselect_b32 s5, s0, 0x810
	v_readlane_b32 s0, v255, 18
	v_readlane_b32 s1, v255, 19
	s_and_b64 s[0:1], s[0:1], exec
	s_cselect_b32 s0, 0x250, s5
	v_readlane_b32 s1, v254, 0
	s_cselect_b32 s40, 0x4b0, s4
	s_add_i32 s41, s1, s0
	v_mov_b32_e32 v32, v156
	s_cmp_ge_i32 s41, s40
	s_cbranch_scc1 .LBB0_955
	s_cmpk_gt_i32 s41, 0x15f
	s_mov_b64 s[24:25], -1
	s_cbranch_scc0 .LBB0_868
	s_cmpk_gt_u32 s41, 0x20f
	s_cbranch_scc0 .LBB0_865
	s_cmpk_gt_u32 s41, 0x28f
	s_cbranch_scc0 .LBB0_862
	s_cmpk_gt_u32 s41, 0x2cf
	s_cbranch_scc0 .LBB0_859
	s_cmpk_gt_u32 s41, 0x30f
	s_cbranch_scc0 .LBB0_856
	s_cmpk_gt_u32 s41, 0x36f
	s_cbranch_scc0 .LBB0_853
	s_cmpk_gt_u32 s41, 0x3af
	s_cbranch_scc0 .LBB0_850
	s_cmpk_gt_u32 s41, 0x50f
	s_cbranch_scc0 .LBB0_847
	s_cmpk_gt_u32 s41, 0x5bf
	s_cbranch_scc0 .LBB0_844
	s_cmpk_gt_u32 s41, 0x61f
	s_cbranch_scc0 .LBB0_841
	s_cmpk_gt_u32 s41, 0x6cf
	s_cbranch_scc0 .LBB0_838
	s_cmpk_gt_u32 s41, 0x70f
	s_cbranch_scc0 .LBB0_835
	s_cmpk_gt_u32 s41, 0x78f
	s_cbranch_scc0 .LBB0_832
	s_cmpk_gt_u32 s41, 0x7cf
	s_cbranch_scc0 .LBB0_829
	s_cmpk_gt_u32 s41, 0x8cf
	s_cbranch_scc0 .LBB0_826
	s_cmpk_gt_u32 s41, 0x92f
	s_cbranch_scc0 .LBB0_823
	s_cmpk_gt_u32 s41, 0x96f
	s_mov_b64 s[4:5], -1
	s_cbranch_scc0 .LBB0_819
	s_load_dwordx2 s[0:1], s[72:73], 0xd0
	s_add_i32 s33, s41, 0xfffff690
	s_mov_b64 s[4:5], 0
	s_waitcnt lgkmcnt(0)
	s_add_u32 s0, s0, 0x4200000
	s_addc_u32 s1, s1, 0
